# P3 carry scan: the 30 loads of each state element requested in one batch before the fma chain (was 15 dependent load/store round trips per element)
# baseline (speedup 1.0000x reference)
; __global__ void __launch_bounds__(NWAVES * 64, 2) fwd(Args args) {
;     ...
;         for (int e = gt; e < NH * HD * HD; e += NGT) {
;             const int h = e >> 14, kv = e & 16383, k = kv >> 7; float Sc = 0.f;
; #pragma unroll
;             for (int sc = 0; sc < 16; ++sc) { const size_t it = (size_t)(h * 16 + sc); HS[(it << 14) + kv] = Sc; Sc = HDt[it * 128 + k] * Sc + HU[(it << 14) + kv]; }
;         }
.LBB0_487:
	v_ashrrev_i32_e32 v9, 10, v8
	v_and_b32_e32 v6, -16, v9
	v_lshrrev_b32_e32 v2, 5, v8
	v_and_b32_e32 v2, 0x1fc, v2
	v_lshlrev_b32_e32 v10, 2, v8
	v_and_b32_e32 v10, 0xfffc, v10
	v_lshl_or_b32 v19, v6, 16, v10
	v_lshl_add_u32 v20, v6, 9, v2
	s_mov_b64 s[26:27], s[12:13]
	s_mov_b64 s[28:29], s[14:15]
	global_load_dword v24, v20, s[28:29]
	s_add_u32 s28, s28, 0x200
	s_addc_u32 s29, s29, 0
	global_load_dword v25, v20, s[28:29]
	s_add_u32 s28, s28, 0x200
	s_addc_u32 s29, s29, 0
	global_load_dword v26, v20, s[28:29]
	s_add_u32 s28, s28, 0x200
	s_addc_u32 s29, s29, 0
	global_load_dword v27, v20, s[28:29]
	s_add_u32 s28, s28, 0x200
	s_addc_u32 s29, s29, 0
	global_load_dword v28, v20, s[28:29]
	s_add_u32 s28, s28, 0x200
	s_addc_u32 s29, s29, 0
	global_load_dword v29, v20, s[28:29]
	s_add_u32 s28, s28, 0x200
	s_addc_u32 s29, s29, 0
	global_load_dword v30, v20, s[28:29]
	s_add_u32 s28, s28, 0x200
	s_addc_u32 s29, s29, 0
	global_load_dword v31, v20, s[28:29]
	s_add_u32 s28, s28, 0x200
	s_addc_u32 s29, s29, 0
	global_load_dword v32, v20, s[28:29]
	s_add_u32 s28, s28, 0x200
	s_addc_u32 s29, s29, 0
	global_load_dword v33, v20, s[28:29]
	s_add_u32 s28, s28, 0x200
	s_addc_u32 s29, s29, 0
	global_load_dword v34, v20, s[28:29]
	s_add_u32 s28, s28, 0x200
	s_addc_u32 s29, s29, 0
	global_load_dword v35, v20, s[28:29]
	s_add_u32 s28, s28, 0x200
	s_addc_u32 s29, s29, 0
	global_load_dword v36, v20, s[28:29]
	s_add_u32 s28, s28, 0x200
	s_addc_u32 s29, s29, 0
	global_load_dword v37, v20, s[28:29]
	s_add_u32 s28, s28, 0x200
	s_addc_u32 s29, s29, 0
	global_load_dword v38, v20, s[28:29]
	s_add_u32 s28, s28, 0x200
	s_addc_u32 s29, s29, 0
	global_load_dword v40, v19, s[26:27]
	s_add_u32 s26, s26, 0x10000
	s_addc_u32 s27, s27, 0
	global_load_dword v41, v19, s[26:27]
	s_add_u32 s26, s26, 0x10000
	s_addc_u32 s27, s27, 0
	global_load_dword v42, v19, s[26:27]
	s_add_u32 s26, s26, 0x10000
	s_addc_u32 s27, s27, 0
	global_load_dword v43, v19, s[26:27]
	s_add_u32 s26, s26, 0x10000
	s_addc_u32 s27, s27, 0
	global_load_dword v44, v19, s[26:27]
	s_add_u32 s26, s26, 0x10000
	s_addc_u32 s27, s27, 0
	global_load_dword v45, v19, s[26:27]
	s_add_u32 s26, s26, 0x10000
	s_addc_u32 s27, s27, 0
	global_load_dword v46, v19, s[26:27]
	s_add_u32 s26, s26, 0x10000
	s_addc_u32 s27, s27, 0
	global_load_dword v47, v19, s[26:27]
	s_add_u32 s26, s26, 0x10000
	s_addc_u32 s27, s27, 0
	global_load_dword v48, v19, s[26:27]
	s_add_u32 s26, s26, 0x10000
	s_addc_u32 s27, s27, 0
	global_load_dword v49, v19, s[26:27]
	s_add_u32 s26, s26, 0x10000
	s_addc_u32 s27, s27, 0
	global_load_dword v50, v19, s[26:27]
	s_add_u32 s26, s26, 0x10000
	s_addc_u32 s27, s27, 0
	global_load_dword v51, v19, s[26:27]
	s_add_u32 s26, s26, 0x10000
	s_addc_u32 s27, s27, 0
	global_load_dword v52, v19, s[26:27]
	s_add_u32 s26, s26, 0x10000
	s_addc_u32 s27, s27, 0
	global_load_dword v53, v19, s[26:27]
	s_add_u32 s26, s26, 0x10000
	s_addc_u32 s27, s27, 0
	global_load_dword v54, v19, s[26:27]
	s_add_u32 s26, s26, 0x10000
	s_addc_u32 s27, s27, 0
	v_add_u32_e32 v8, s81, v8
	v_cmp_lt_i32_e32 vcc, s6, v8
	s_or_b64 s[4:5], vcc, s[4:5]
	s_mov_b64 s[26:27], s[8:9]
	s_waitcnt vmcnt(0)
	v_fmac_f32_e32 v40, 0, v24
	global_store_dword v19, v3, s[26:27]
	s_add_u32 s26, s26, 0x10000
	s_addc_u32 s27, s27, 0
	global_store_dword v19, v40, s[26:27]
	v_fmac_f32_e32 v41, v40, v25
	s_add_u32 s26, s26, 0x10000
	s_addc_u32 s27, s27, 0
	global_store_dword v19, v41, s[26:27]
	v_fmac_f32_e32 v42, v41, v26
	s_add_u32 s26, s26, 0x10000
	s_addc_u32 s27, s27, 0
	global_store_dword v19, v42, s[26:27]
	v_fmac_f32_e32 v43, v42, v27
	s_add_u32 s26, s26, 0x10000
	s_addc_u32 s27, s27, 0
	global_store_dword v19, v43, s[26:27]
	v_fmac_f32_e32 v44, v43, v28
	s_add_u32 s26, s26, 0x10000
	s_addc_u32 s27, s27, 0
	global_store_dword v19, v44, s[26:27]
	v_fmac_f32_e32 v45, v44, v29
	s_add_u32 s26, s26, 0x10000
	s_addc_u32 s27, s27, 0
	global_store_dword v19, v45, s[26:27]
	v_fmac_f32_e32 v46, v45, v30
	s_add_u32 s26, s26, 0x10000
	s_addc_u32 s27, s27, 0
	global_store_dword v19, v46, s[26:27]
	v_fmac_f32_e32 v47, v46, v31
	s_add_u32 s26, s26, 0x10000
	s_addc_u32 s27, s27, 0
	global_store_dword v19, v47, s[26:27]
	v_fmac_f32_e32 v48, v47, v32
	s_add_u32 s26, s26, 0x10000
	s_addc_u32 s27, s27, 0
	global_store_dword v19, v48, s[26:27]
	v_fmac_f32_e32 v49, v48, v33
	s_add_u32 s26, s26, 0x10000
	s_addc_u32 s27, s27, 0
	global_store_dword v19, v49, s[26:27]
	v_fmac_f32_e32 v50, v49, v34
	s_add_u32 s26, s26, 0x10000
	s_addc_u32 s27, s27, 0
	global_store_dword v19, v50, s[26:27]
	v_fmac_f32_e32 v51, v50, v35
	s_add_u32 s26, s26, 0x10000
	s_addc_u32 s27, s27, 0
	global_store_dword v19, v51, s[26:27]
	v_fmac_f32_e32 v52, v51, v36
	s_add_u32 s26, s26, 0x10000
	s_addc_u32 s27, s27, 0
	global_store_dword v19, v52, s[26:27]
	v_fmac_f32_e32 v53, v52, v37
	s_add_u32 s26, s26, 0x10000
	s_addc_u32 s27, s27, 0
	global_store_dword v19, v53, s[26:27]
	v_fmac_f32_e32 v54, v53, v38
	s_add_u32 s26, s26, 0x10000
	s_addc_u32 s27, s27, 0
	global_store_dword v19, v54, s[26:27]
	s_andn2_b64 exec, exec, s[4:5]
	s_cbranch_execnz .LBB0_487
